# v60: barrier non-leader back-off s_sleep 20
# baseline (speedup 1.0000x reference)
; __device__ __forceinline__ unsigned xb_ld(unsigned* p)              { return __hip_atomic_load(p, __ATOMIC_RELAXED, __HIP_MEMORY_SCOPE_AGENT); }
; #define XB_SPIN(cond, bar) do { unsigned _sp = 0; while (cond) { __builtin_amdgcn_s_sleep(1); \
;     if ((++_sp & 255u) == 0u) { if (xb_ld(&(bar)[XB_TMO])) break; if (_sp > XB_SPIN_CAP) { atomicAdd(&(bar)[XB_TMO], 1u); break; } } } } while (0)
; __device__ __forceinline__ void xcd_barrier(const XcdBarrier& b) {
;     ...
;             XB_SPIN(xb_ld(&bar[XB_XGEN(b.x)]) == gen, bar);
.Lxb0_wait:
	s_sleep 20
